# half-tile rounds of FFN-up and the mLSTM q/k GEMM also skip the LDS-DMA loads of the unused activation row half
# baseline (speedup 1.0000x reference)
.LBB0_56:
	s_add_u32 s8, s6, 0xfffc0080
	s_addc_u32 s9, s7, -1
	s_add_i32 s41, 0, 0x10000
	v_add_u32_e32 v0, s41, v169
	ds_read_b128 v[66:69], v0
	ds_read_b128 v[70:73], v0 offset:1024
	ds_read_b128 v[74:77], v0 offset:2048
	ds_read_b128 v[78:81], v0 offset:3072
	s_cmp_eq_u32 s40, 12
	s_cselect_b32 s11, s14, s9
	s_cselect_b32 s10, s15, s8
	s_cselect_b32 s9, s16, s25
	s_cselect_b32 s8, s17, s23
	v_lshl_add_u64 v[200:201], s[6:7], 0, v[182:183]
	s_add_i32 m0, s44, 0xc000
	ds_read_b128 v[82:85], v229
	ds_read_b128 v[86:89], v229 offset:1024
	ds_read_b128 v[90:93], v229 offset:2048
	ds_read_b128 v[94:97], v229 offset:3072
	ds_read_b128 v[184:187], v229 offset:4096
	ds_read_b128 v[188:191], v229 offset:5120
	ds_read_b128 v[192:195], v229 offset:6144
	ds_read_b128 v[196:199], v229 offset:7168
	s_cmp_lg_u32 s99, 0
	s_cbranch_scc1 .Lhsd1_0
	global_load_lds_dwordx4 v[200:201], off
.Lhsd1_0:
	v_lshl_add_u64 v[200:201], s[6:7], 0, v[180:181]
	s_add_i32 m0, s44, 0xe000
	s_nop 0
	s_cmp_lg_u32 s99, 0
	s_cbranch_scc1 .Lhsd1_1
	global_load_lds_dwordx4 v[200:201], off
.Lhsd1_1:
	s_waitcnt lgkmcnt(8)
	s_barrier
	s_waitcnt lgkmcnt(0)
	s_setprio 1
	s_waitcnt lgkmcnt(0)
	v_mfma_f32_16x16x32_bf16 v[158:161], v[66:69], v[82:85], v[158:161]
	v_mfma_f32_16x16x32_bf16 v[154:157], v[74:77], v[82:85], v[154:157]
	v_mfma_f32_16x16x32_bf16 v[146:149], v[66:69], v[90:93], v[146:149]
	v_mfma_f32_16x16x32_bf16 v[138:141], v[74:77], v[90:93], v[138:141]
	v_mfma_f32_16x16x32_bf16 v[130:133], v[66:69], v[184:187], v[130:133]
	v_mfma_f32_16x16x32_bf16 v[122:125], v[74:77], v[184:187], v[122:125]
	v_mfma_f32_16x16x32_bf16 v[110:113], v[66:69], v[192:195], v[110:113]
	v_mfma_f32_16x16x32_bf16 v[106:109], v[74:77], v[192:195], v[106:109]
	v_mfma_f32_16x16x32_bf16 v[158:161], v[70:73], v[86:89], v[158:161]
	v_mfma_f32_16x16x32_bf16 v[154:157], v[78:81], v[86:89], v[154:157]
	v_mfma_f32_16x16x32_bf16 v[146:149], v[70:73], v[94:97], v[146:149]
	v_mfma_f32_16x16x32_bf16 v[138:141], v[78:81], v[94:97], v[138:141]
	v_mfma_f32_16x16x32_bf16 v[130:133], v[70:73], v[188:191], v[130:133]
	v_mfma_f32_16x16x32_bf16 v[122:125], v[78:81], v[188:191], v[122:125]
	v_mfma_f32_16x16x32_bf16 v[110:113], v[70:73], v[196:199], v[110:113]
	v_mfma_f32_16x16x32_bf16 v[106:109], v[78:81], v[196:199], v[106:109]
	s_setprio 0
	s_barrier
	s_add_i32 s53, 0, 0x14000
	s_add_i32 s41, s41, s43
	v_add_u32_e32 v0, s53, v169
	v_lshl_add_u64 v[200:201], s[8:9], 0, v[176:177]
	s_mov_b32 m0, s41
	ds_read_b128 v[230:233], v0
	ds_read_b128 v[234:237], v0 offset:1024
	ds_read_b128 v[238:241], v0 offset:2048
	ds_read_b128 v[242:245], v0 offset:3072
	global_load_lds_dwordx4 v[200:201], off
	v_lshl_add_u64 v[210:211], s[8:9], 0, v[178:179]
	s_add_i32 m0, s41, 0x2000
	s_nop 0
	global_load_lds_dwordx4 v[210:211], off
	s_barrier
	s_waitcnt lgkmcnt(0)
	s_setprio 1
	s_waitcnt lgkmcnt(0)
	v_mfma_f32_16x16x32_bf16 v[150:153], v[230:233], v[82:85], v[150:153]
	v_mfma_f32_16x16x32_bf16 v[82:85], v[238:241], v[82:85], v[142:145]
	v_mfma_f32_16x16x32_bf16 v[150:153], v[234:237], v[86:89], v[150:153]
	v_mfma_f32_16x16x32_bf16 v[82:85], v[242:245], v[86:89], v[82:85]
	v_mfma_f32_16x16x32_bf16 v[86:89], v[230:233], v[90:93], v[134:137]
	v_mfma_f32_16x16x32_bf16 v[90:93], v[238:241], v[90:93], v[126:129]
	v_mfma_f32_16x16x32_bf16 v[114:117], v[238:241], v[184:187], v[114:117]
	v_mfma_f32_16x16x32_bf16 v[102:105], v[230:233], v[192:195], v[102:105]
	v_mfma_f32_16x16x32_bf16 v[98:101], v[238:241], v[192:195], v[98:101]
	v_mfma_f32_16x16x32_bf16 v[86:89], v[234:237], v[94:97], v[86:89]
	v_mfma_f32_16x16x32_bf16 v[90:93], v[242:245], v[94:97], v[90:93]
	v_mfma_f32_16x16x32_bf16 v[94:97], v[230:233], v[184:187], v[118:121]
	v_mfma_f32_16x16x32_bf16 v[114:117], v[242:245], v[188:191], v[114:117]
	v_mfma_f32_16x16x32_bf16 v[102:105], v[234:237], v[196:199], v[102:105]
	v_mfma_f32_16x16x32_bf16 v[98:101], v[242:245], v[196:199], v[98:101]
	v_mfma_f32_16x16x32_bf16 v[94:97], v[234:237], v[188:191], v[94:97]
	s_setprio 0
	s_mov_b32 m0, s44
	v_lshl_add_u64 v[172:173], s[10:11], 0, v[176:177]
	s_barrier
	ds_read_b128 v[118:121], v229 offset:16384
	ds_read_b128 v[126:129], v229 offset:17408
	ds_read_b128 v[134:137], v229 offset:18432
	ds_read_b128 v[142:145], v229 offset:19456
	ds_read_b128 v[184:187], v229 offset:20480
	ds_read_b128 v[188:191], v229 offset:21504
	ds_read_b128 v[192:195], v229 offset:22528
	ds_read_b128 v[196:199], v229 offset:23552
	global_load_lds_dwordx4 v[172:173], off
	v_lshl_add_u64 v[174:175], s[10:11], 0, v[178:179]
	s_mov_b32 m0, s45
	s_nop 0
	global_load_lds_dwordx4 v[174:175], off
	s_barrier
	s_waitcnt lgkmcnt(0)
	s_setprio 1
	s_waitcnt lgkmcnt(0)
	s_cmp_lg_u32 s99, 0
	s_cbranch_scc1 .Lfu_skip3
	v_mfma_f32_16x16x32_bf16 v[62:65], v[66:69], v[118:121], v[62:65]
	v_mfma_f32_16x16x32_bf16 v[58:61], v[74:77], v[118:121], v[58:61]
	v_mfma_f32_16x16x32_bf16 v[50:53], v[66:69], v[134:137], v[50:53]
	v_mfma_f32_16x16x32_bf16 v[42:45], v[74:77], v[134:137], v[42:45]
	v_mfma_f32_16x16x32_bf16 v[34:37], v[66:69], v[184:187], v[34:37]
	v_mfma_f32_16x16x32_bf16 v[26:29], v[74:77], v[184:187], v[26:29]
	v_mfma_f32_16x16x32_bf16 v[14:17], v[66:69], v[192:195], v[14:17]
	v_mfma_f32_16x16x32_bf16 v[10:13], v[74:77], v[192:195], v[10:13]
	v_mfma_f32_16x16x32_bf16 v[62:65], v[70:73], v[126:129], v[62:65]
	v_mfma_f32_16x16x32_bf16 v[58:61], v[78:81], v[126:129], v[58:61]
	v_mfma_f32_16x16x32_bf16 v[50:53], v[70:73], v[142:145], v[50:53]
	v_mfma_f32_16x16x32_bf16 v[42:45], v[78:81], v[142:145], v[42:45]
	v_mfma_f32_16x16x32_bf16 v[34:37], v[70:73], v[188:191], v[34:37]
	v_mfma_f32_16x16x32_bf16 v[26:29], v[78:81], v[188:191], v[26:29]
	v_mfma_f32_16x16x32_bf16 v[14:17], v[70:73], v[196:199], v[14:17]
	v_mfma_f32_16x16x32_bf16 v[10:13], v[78:81], v[196:199], v[10:13]

.Lfu_skip4:
	s_setprio 0
	s_add_i32 s41, 0, 0x18000
	v_add_u32_e32 v0, s41, v169
	s_barrier
	ds_read_b128 v[66:69], v0
	ds_read_b128 v[70:73], v0 offset:1024
	ds_read_b128 v[74:77], v0 offset:2048
	ds_read_b128 v[78:81], v0 offset:3072
	s_add_u32 s10, s10, 0x40000
	s_addc_u32 s11, s11, 0
	s_mov_b32 m0, s46
	v_lshl_add_u64 v[134:135], s[10:11], 0, v[176:177]
	ds_read_b128 v[118:121], v229 offset:32768
	ds_read_b128 v[126:129], v229 offset:33792
	ds_read_b128 v[184:187], v229 offset:34816
	ds_read_b128 v[188:191], v229 offset:35840
	ds_read_b128 v[192:195], v229 offset:36864
	ds_read_b128 v[196:199], v229 offset:37888
	ds_read_b128 v[230:233], v229 offset:38912
	ds_read_b128 v[234:237], v229 offset:39936
	s_cmp_lg_u32 s99, 0
	s_cbranch_scc1 .Lhsd1_2
	global_load_lds_dwordx4 v[134:135], off
.Lhsd1_2:
	v_lshl_add_u64 v[134:135], s[10:11], 0, v[178:179]
	s_mov_b32 m0, s47
	s_nop 0
	s_cmp_lg_u32 s99, 0
	s_cbranch_scc1 .Lhsd1_3
	global_load_lds_dwordx4 v[134:135], off
.Lhsd1_3:
	s_waitcnt lgkmcnt(8)
	s_barrier
	s_waitcnt lgkmcnt(0)
	s_setprio 1
	s_waitcnt lgkmcnt(0)
	v_mfma_f32_16x16x32_bf16 v[134:137], v[66:69], v[118:121], v[158:161]
	v_mfma_f32_16x16x32_bf16 v[158:161], v[70:73], v[126:129], v[134:137]
	v_mfma_f32_16x16x32_bf16 v[134:137], v[74:77], v[118:121], v[154:157]
	v_mfma_f32_16x16x32_bf16 v[154:157], v[78:81], v[126:129], v[134:137]
	v_mfma_f32_16x16x32_bf16 v[134:137], v[66:69], v[184:187], v[146:149]
	v_mfma_f32_16x16x32_bf16 v[146:149], v[70:73], v[188:191], v[134:137]
	v_mfma_f32_16x16x32_bf16 v[134:137], v[74:77], v[184:187], v[138:141]
	v_mfma_f32_16x16x32_bf16 v[130:133], v[66:69], v[192:195], v[130:133]
	v_mfma_f32_16x16x32_bf16 v[122:125], v[74:77], v[192:195], v[122:125]
	v_mfma_f32_16x16x32_bf16 v[110:113], v[66:69], v[230:233], v[110:113]
	v_mfma_f32_16x16x32_bf16 v[106:109], v[74:77], v[230:233], v[106:109]
	v_mfma_f32_16x16x32_bf16 v[138:141], v[78:81], v[188:191], v[134:137]
	v_mfma_f32_16x16x32_bf16 v[130:133], v[70:73], v[196:199], v[130:133]
	v_mfma_f32_16x16x32_bf16 v[122:125], v[78:81], v[196:199], v[122:125]
	v_mfma_f32_16x16x32_bf16 v[110:113], v[70:73], v[234:237], v[110:113]
	v_mfma_f32_16x16x32_bf16 v[106:109], v[78:81], v[234:237], v[106:109]
	s_setprio 0
	s_barrier
	s_add_i32 s10, 0, 0x1c000
	s_add_i32 s11, s41, s43
	v_add_u32_e32 v0, s10, v169
	v_lshl_add_u64 v[134:135], v[200:201], 0, s[92:93]
	s_mov_b32 m0, s11
	ds_read_b128 v[238:241], v0
	ds_read_b128 v[242:245], v0 offset:1024
	ds_read_b128 v[246:249], v0 offset:2048
	ds_read_b128 v[250:253], v0 offset:3072
	global_load_lds_dwordx4 v[134:135], off
	v_lshl_add_u64 v[134:135], v[210:211], 0, s[92:93]
	s_add_i32 m0, s11, 0x2000
	s_nop 0
	global_load_lds_dwordx4 v[134:135], off
	s_barrier
	s_waitcnt lgkmcnt(0)
	s_setprio 1
	s_waitcnt lgkmcnt(0)
	v_mfma_f32_16x16x32_bf16 v[82:85], v[246:249], v[118:121], v[82:85]
	v_mfma_f32_16x16x32_bf16 v[134:137], v[238:241], v[118:121], v[150:153]
	v_mfma_f32_16x16x32_bf16 v[142:145], v[250:253], v[126:129], v[82:85]
	v_mfma_f32_16x16x32_bf16 v[82:85], v[238:241], v[184:187], v[86:89]
	v_mfma_f32_16x16x32_bf16 v[150:153], v[242:245], v[126:129], v[134:137]
	v_mfma_f32_16x16x32_bf16 v[134:137], v[242:245], v[188:191], v[82:85]
	v_mfma_f32_16x16x32_bf16 v[82:85], v[246:249], v[184:187], v[90:93]
	v_mfma_f32_16x16x32_bf16 v[126:129], v[250:253], v[188:191], v[82:85]
	v_mfma_f32_16x16x32_bf16 v[82:85], v[238:241], v[192:195], v[94:97]
	v_mfma_f32_16x16x32_bf16 v[118:121], v[242:245], v[196:199], v[82:85]
	v_mfma_f32_16x16x32_bf16 v[82:85], v[246:249], v[192:195], v[114:117]
	v_mfma_f32_16x16x32_bf16 v[114:117], v[250:253], v[196:199], v[82:85]
	v_mfma_f32_16x16x32_bf16 v[82:85], v[238:241], v[230:233], v[102:105]
	v_mfma_f32_16x16x32_bf16 v[102:105], v[242:245], v[234:237], v[82:85]
	v_mfma_f32_16x16x32_bf16 v[82:85], v[246:249], v[230:233], v[98:101]
	v_mfma_f32_16x16x32_bf16 v[98:101], v[250:253], v[234:237], v[82:85]
	s_setprio 0
	s_mov_b32 m0, s48
	v_lshl_add_u64 v[172:173], v[172:173], 0, s[92:93]
	s_barrier
	s_nop 2
	ds_read_b128 v[82:85], v229 offset:49152
	ds_read_b128 v[86:89], v229 offset:50176
	ds_read_b128 v[90:93], v229 offset:51200
	ds_read_b128 v[94:97], v229 offset:52224
	ds_read_b128 v[184:187], v229 offset:53248
	ds_read_b128 v[188:191], v229 offset:54272
	ds_read_b128 v[192:195], v229 offset:55296
	ds_read_b128 v[196:199], v229 offset:56320
	global_load_lds_dwordx4 v[172:173], off
	v_lshl_add_u64 v[172:173], v[174:175], 0, s[92:93]
	s_mov_b32 m0, s49
	s_nop 0
	global_load_lds_dwordx4 v[172:173], off
	s_barrier
	s_waitcnt lgkmcnt(0)
	s_setprio 1
	s_waitcnt lgkmcnt(0)
	s_cmp_lg_u32 s99, 0
	s_cbranch_scc1 .Lfu_skip7
	v_mfma_f32_16x16x32_bf16 v[62:65], v[66:69], v[82:85], v[62:65]
	v_mfma_f32_16x16x32_bf16 v[58:61], v[74:77], v[82:85], v[58:61]
	v_mfma_f32_16x16x32_bf16 v[50:53], v[66:69], v[90:93], v[50:53]
	v_mfma_f32_16x16x32_bf16 v[42:45], v[74:77], v[90:93], v[42:45]
	v_mfma_f32_16x16x32_bf16 v[34:37], v[66:69], v[184:187], v[34:37]
	v_mfma_f32_16x16x32_bf16 v[26:29], v[74:77], v[184:187], v[26:29]
	v_mfma_f32_16x16x32_bf16 v[14:17], v[66:69], v[192:195], v[14:17]
	v_mfma_f32_16x16x32_bf16 v[10:13], v[74:77], v[192:195], v[10:13]
	v_mfma_f32_16x16x32_bf16 v[62:65], v[70:73], v[86:89], v[62:65]
	v_mfma_f32_16x16x32_bf16 v[58:61], v[78:81], v[86:89], v[58:61]
	v_mfma_f32_16x16x32_bf16 v[50:53], v[70:73], v[94:97], v[50:53]
	v_mfma_f32_16x16x32_bf16 v[42:45], v[78:81], v[94:97], v[42:45]
	v_mfma_f32_16x16x32_bf16 v[34:37], v[70:73], v[188:191], v[34:37]
	v_mfma_f32_16x16x32_bf16 v[26:29], v[78:81], v[188:191], v[26:29]
	v_mfma_f32_16x16x32_bf16 v[14:17], v[70:73], v[196:199], v[14:17]
	v_mfma_f32_16x16x32_bf16 v[10:13], v[78:81], v[196:199], v[10:13]

.LBB0_893:
	s_add_u32 s20, s8, 0xfffe0080
	s_addc_u32 s21, s9, -1
	s_add_i32 s44, 0, 0x10000
	v_add_u32_e32 v150, s44, v136
	ds_read_b128 v[138:141], v150
	ds_read_b128 v[142:145], v150 offset:1024
	ds_read_b128 v[146:149], v150 offset:2048
	ds_read_b128 v[150:153], v150 offset:3072
	s_cmp_eq_u32 s43, 0
	s_cselect_b32 s23, s13, s21
	s_cselect_b32 s22, s39, s20
	s_cselect_b32 s21, s11, s42
	s_cselect_b32 s20, s40, s41
	v_lshl_add_u64 v[200:201], s[8:9], 0, v[134:135]
	s_add_i32 m0, s29, 0xc000
	ds_read_b128 v[154:157], v137
	ds_read_b128 v[158:161], v137 offset:1024
	ds_read_b128 v[176:179], v137 offset:2048
	ds_read_b128 v[180:183], v137 offset:3072
	ds_read_b128 v[184:187], v137 offset:4096
	ds_read_b128 v[188:191], v137 offset:5120
	ds_read_b128 v[192:195], v137 offset:6144
	ds_read_b128 v[196:199], v137 offset:7168
	s_cmp_lg_u32 s99, 0
	s_cbranch_scc1 .Lhsd2_0
	global_load_lds_dwordx4 v[200:201], off
.Lhsd2_0:
	v_lshl_add_u64 v[200:201], s[8:9], 0, v[132:133]
	s_add_i32 m0, s29, 0xe000
	s_nop 0
	s_cmp_lg_u32 s99, 0
	s_cbranch_scc1 .Lhsd2_1
	global_load_lds_dwordx4 v[200:201], off
.Lhsd2_1:
	s_waitcnt lgkmcnt(8)
	s_barrier
	s_waitcnt lgkmcnt(0)
	s_setprio 1
	s_waitcnt lgkmcnt(0)
	v_mfma_f32_16x16x32_bf16 v[126:129], v[138:141], v[154:157], v[126:129]
	v_mfma_f32_16x16x32_bf16 v[122:125], v[146:149], v[154:157], v[122:125]
	v_mfma_f32_16x16x32_bf16 v[114:117], v[138:141], v[176:179], v[114:117]
	v_mfma_f32_16x16x32_bf16 v[106:109], v[146:149], v[176:179], v[106:109]
	v_mfma_f32_16x16x32_bf16 v[98:101], v[138:141], v[184:187], v[98:101]
	v_mfma_f32_16x16x32_bf16 v[90:93], v[146:149], v[184:187], v[90:93]
	v_mfma_f32_16x16x32_bf16 v[82:85], v[138:141], v[192:195], v[82:85]
	v_mfma_f32_16x16x32_bf16 v[74:77], v[146:149], v[192:195], v[74:77]
	v_mfma_f32_16x16x32_bf16 v[126:129], v[142:145], v[158:161], v[126:129]
	v_mfma_f32_16x16x32_bf16 v[122:125], v[150:153], v[158:161], v[122:125]
	v_mfma_f32_16x16x32_bf16 v[114:117], v[142:145], v[180:183], v[114:117]
	v_mfma_f32_16x16x32_bf16 v[106:109], v[150:153], v[180:183], v[106:109]
	v_mfma_f32_16x16x32_bf16 v[98:101], v[142:145], v[188:191], v[98:101]
	v_mfma_f32_16x16x32_bf16 v[90:93], v[150:153], v[188:191], v[90:93]
	v_mfma_f32_16x16x32_bf16 v[82:85], v[142:145], v[196:199], v[82:85]
	v_mfma_f32_16x16x32_bf16 v[74:77], v[150:153], v[196:199], v[74:77]
	s_setprio 0
	s_barrier
	s_add_i32 s46, 0, 0x14000
	s_add_i32 s44, s44, s27
	v_add_u32_e32 v169, s46, v136
	v_lshl_add_u64 v[200:201], s[20:21], 0, v[0:1]
	s_mov_b32 m0, s44
	ds_read_b128 v[230:233], v169
	ds_read_b128 v[234:237], v169 offset:1024
	ds_read_b128 v[238:241], v169 offset:2048
	ds_read_b128 v[242:245], v169 offset:3072
	global_load_lds_dwordx4 v[200:201], off
	v_lshl_add_u64 v[246:247], s[20:21], 0, v[130:131]
	s_add_i32 m0, s44, 0x2000
	s_nop 0
	global_load_lds_dwordx4 v[246:247], off
	s_barrier
	s_waitcnt lgkmcnt(0)
	s_setprio 1
	s_waitcnt lgkmcnt(0)
	v_mfma_f32_16x16x32_bf16 v[118:121], v[230:233], v[154:157], v[118:121]
	v_mfma_f32_16x16x32_bf16 v[110:113], v[238:241], v[154:157], v[110:113]
	v_mfma_f32_16x16x32_bf16 v[102:105], v[230:233], v[176:179], v[102:105]
	v_mfma_f32_16x16x32_bf16 v[94:97], v[238:241], v[176:179], v[94:97]
	v_mfma_f32_16x16x32_bf16 v[86:89], v[230:233], v[184:187], v[86:89]
	v_mfma_f32_16x16x32_bf16 v[78:81], v[238:241], v[184:187], v[78:81]
	v_mfma_f32_16x16x32_bf16 v[70:73], v[230:233], v[192:195], v[70:73]
	v_mfma_f32_16x16x32_bf16 v[66:69], v[238:241], v[192:195], v[66:69]
	v_mfma_f32_16x16x32_bf16 v[118:121], v[234:237], v[158:161], v[118:121]
	v_mfma_f32_16x16x32_bf16 v[110:113], v[242:245], v[158:161], v[110:113]
	v_mfma_f32_16x16x32_bf16 v[102:105], v[234:237], v[180:183], v[102:105]
	v_mfma_f32_16x16x32_bf16 v[94:97], v[242:245], v[180:183], v[94:97]
	v_mfma_f32_16x16x32_bf16 v[86:89], v[234:237], v[188:191], v[86:89]
	v_mfma_f32_16x16x32_bf16 v[78:81], v[242:245], v[188:191], v[78:81]
	v_mfma_f32_16x16x32_bf16 v[70:73], v[234:237], v[196:199], v[70:73]
	v_mfma_f32_16x16x32_bf16 v[66:69], v[242:245], v[196:199], v[66:69]
	s_setprio 0
	s_mov_b32 m0, s29
	v_lshl_add_u64 v[248:249], s[22:23], 0, v[0:1]
	s_barrier
	ds_read_b128 v[154:157], v137 offset:16384
	ds_read_b128 v[158:161], v137 offset:17408
	ds_read_b128 v[176:179], v137 offset:18432
	ds_read_b128 v[180:183], v137 offset:19456
	ds_read_b128 v[184:187], v137 offset:20480
	ds_read_b128 v[188:191], v137 offset:21504
	ds_read_b128 v[192:195], v137 offset:22528
	ds_read_b128 v[196:199], v137 offset:23552
	global_load_lds_dwordx4 v[248:249], off
	v_lshl_add_u64 v[250:251], s[22:23], 0, v[130:131]
	s_mov_b32 m0, s30
	s_nop 0
	global_load_lds_dwordx4 v[250:251], off
	s_barrier
	s_waitcnt lgkmcnt(0)
	s_setprio 1
	s_waitcnt lgkmcnt(0)
	s_cmp_lg_u32 s99, 0
	s_cbranch_scc1 .La3_skip3
	v_mfma_f32_16x16x32_bf16 v[62:65], v[138:141], v[154:157], v[62:65]
	v_mfma_f32_16x16x32_bf16 v[58:61], v[146:149], v[154:157], v[58:61]
	v_mfma_f32_16x16x32_bf16 v[50:53], v[138:141], v[176:179], v[50:53]
	v_mfma_f32_16x16x32_bf16 v[42:45], v[146:149], v[176:179], v[42:45]
	v_mfma_f32_16x16x32_bf16 v[34:37], v[138:141], v[184:187], v[34:37]
	v_mfma_f32_16x16x32_bf16 v[26:29], v[146:149], v[184:187], v[26:29]
	v_mfma_f32_16x16x32_bf16 v[18:21], v[138:141], v[192:195], v[18:21]
	v_mfma_f32_16x16x32_bf16 v[10:13], v[146:149], v[192:195], v[10:13]
	v_mfma_f32_16x16x32_bf16 v[62:65], v[142:145], v[158:161], v[62:65]
	v_mfma_f32_16x16x32_bf16 v[58:61], v[150:153], v[158:161], v[58:61]
	v_mfma_f32_16x16x32_bf16 v[50:53], v[142:145], v[180:183], v[50:53]
	v_mfma_f32_16x16x32_bf16 v[42:45], v[150:153], v[180:183], v[42:45]
	v_mfma_f32_16x16x32_bf16 v[34:37], v[142:145], v[188:191], v[34:37]
	v_mfma_f32_16x16x32_bf16 v[26:29], v[150:153], v[188:191], v[26:29]
	v_mfma_f32_16x16x32_bf16 v[18:21], v[142:145], v[196:199], v[18:21]
	v_mfma_f32_16x16x32_bf16 v[10:13], v[150:153], v[196:199], v[10:13]

.La3_skip4:
	s_setprio 0
	s_add_i32 s44, 0, 0x18000
	v_add_u32_e32 v150, s44, v136
	s_barrier
	ds_read_b128 v[138:141], v150
	ds_read_b128 v[142:145], v150 offset:1024
	ds_read_b128 v[146:149], v150 offset:2048
	ds_read_b128 v[150:153], v150 offset:3072
	s_add_u32 s22, s22, 0x20000
	s_addc_u32 s23, s23, 0
	s_mov_b32 m0, s31
	v_lshl_add_u64 v[230:231], s[22:23], 0, v[0:1]
	ds_read_b128 v[154:157], v137 offset:32768
	ds_read_b128 v[158:161], v137 offset:33792
	ds_read_b128 v[176:179], v137 offset:34816
	ds_read_b128 v[180:183], v137 offset:35840
	ds_read_b128 v[184:187], v137 offset:36864
	ds_read_b128 v[188:191], v137 offset:37888
	ds_read_b128 v[192:195], v137 offset:38912
	ds_read_b128 v[196:199], v137 offset:39936
	s_cmp_lg_u32 s99, 0
	s_cbranch_scc1 .Lhsd2_2
	global_load_lds_dwordx4 v[230:231], off
.Lhsd2_2:
	v_lshl_add_u64 v[230:231], s[22:23], 0, v[130:131]
	s_mov_b32 m0, s34
	s_nop 0
	s_cmp_lg_u32 s99, 0
	s_cbranch_scc1 .Lhsd2_3
	global_load_lds_dwordx4 v[230:231], off
.Lhsd2_3:
	s_waitcnt lgkmcnt(8)
	s_barrier
	s_waitcnt lgkmcnt(0)
	s_setprio 1
	s_waitcnt lgkmcnt(0)
	v_mfma_f32_16x16x32_bf16 v[126:129], v[138:141], v[154:157], v[126:129]
	v_mfma_f32_16x16x32_bf16 v[122:125], v[146:149], v[154:157], v[122:125]
	v_mfma_f32_16x16x32_bf16 v[114:117], v[138:141], v[176:179], v[114:117]
	v_mfma_f32_16x16x32_bf16 v[106:109], v[146:149], v[176:179], v[106:109]
	v_mfma_f32_16x16x32_bf16 v[98:101], v[138:141], v[184:187], v[98:101]
	v_mfma_f32_16x16x32_bf16 v[90:93], v[146:149], v[184:187], v[90:93]
	v_mfma_f32_16x16x32_bf16 v[82:85], v[138:141], v[192:195], v[82:85]
	v_mfma_f32_16x16x32_bf16 v[74:77], v[146:149], v[192:195], v[74:77]
	v_mfma_f32_16x16x32_bf16 v[126:129], v[142:145], v[158:161], v[126:129]
	v_mfma_f32_16x16x32_bf16 v[122:125], v[150:153], v[158:161], v[122:125]
	v_mfma_f32_16x16x32_bf16 v[114:117], v[142:145], v[180:183], v[114:117]
	v_mfma_f32_16x16x32_bf16 v[106:109], v[150:153], v[180:183], v[106:109]
	v_mfma_f32_16x16x32_bf16 v[98:101], v[142:145], v[188:191], v[98:101]
	v_mfma_f32_16x16x32_bf16 v[90:93], v[150:153], v[188:191], v[90:93]
	v_mfma_f32_16x16x32_bf16 v[82:85], v[142:145], v[196:199], v[82:85]
	v_mfma_f32_16x16x32_bf16 v[74:77], v[150:153], v[196:199], v[74:77]
	s_setprio 0
	s_barrier
	s_add_i32 s22, 0, 0x1c000
	s_add_i32 s23, s44, s27
	v_add_u32_e32 v169, s22, v136
	v_lshl_add_u64 v[200:201], v[200:201], 0, s[92:93]
	s_mov_b32 m0, s23
	ds_read_b128 v[230:233], v169
	ds_read_b128 v[234:237], v169 offset:1024
	ds_read_b128 v[238:241], v169 offset:2048
	ds_read_b128 v[242:245], v169 offset:3072
	global_load_lds_dwordx4 v[200:201], off
	v_lshl_add_u64 v[200:201], v[246:247], 0, s[92:93]
	s_add_i32 m0, s23, 0x2000
	s_nop 0
	global_load_lds_dwordx4 v[200:201], off
	s_barrier
	s_waitcnt lgkmcnt(0)
	s_setprio 1
	s_waitcnt lgkmcnt(0)
	v_mfma_f32_16x16x32_bf16 v[118:121], v[230:233], v[154:157], v[118:121]
	v_mfma_f32_16x16x32_bf16 v[110:113], v[238:241], v[154:157], v[110:113]
	v_mfma_f32_16x16x32_bf16 v[102:105], v[230:233], v[176:179], v[102:105]
	v_mfma_f32_16x16x32_bf16 v[94:97], v[238:241], v[176:179], v[94:97]
	v_mfma_f32_16x16x32_bf16 v[86:89], v[230:233], v[184:187], v[86:89]
	v_mfma_f32_16x16x32_bf16 v[78:81], v[238:241], v[184:187], v[78:81]
	v_mfma_f32_16x16x32_bf16 v[70:73], v[230:233], v[192:195], v[70:73]
	v_mfma_f32_16x16x32_bf16 v[66:69], v[238:241], v[192:195], v[66:69]
	v_mfma_f32_16x16x32_bf16 v[118:121], v[234:237], v[158:161], v[118:121]
	v_mfma_f32_16x16x32_bf16 v[110:113], v[242:245], v[158:161], v[110:113]
	v_mfma_f32_16x16x32_bf16 v[102:105], v[234:237], v[180:183], v[102:105]
	v_mfma_f32_16x16x32_bf16 v[94:97], v[242:245], v[180:183], v[94:97]
	v_mfma_f32_16x16x32_bf16 v[86:89], v[234:237], v[188:191], v[86:89]
	v_mfma_f32_16x16x32_bf16 v[78:81], v[242:245], v[188:191], v[78:81]
	v_mfma_f32_16x16x32_bf16 v[70:73], v[234:237], v[196:199], v[70:73]
	v_mfma_f32_16x16x32_bf16 v[66:69], v[242:245], v[196:199], v[66:69]
	s_setprio 0
	s_mov_b32 m0, s35
	v_lshl_add_u64 v[200:201], v[248:249], 0, s[92:93]
	s_barrier
	ds_read_b128 v[154:157], v137 offset:49152
	ds_read_b128 v[158:161], v137 offset:50176
	ds_read_b128 v[176:179], v137 offset:51200
	ds_read_b128 v[180:183], v137 offset:52224
	ds_read_b128 v[184:187], v137 offset:53248
	ds_read_b128 v[188:191], v137 offset:54272
	ds_read_b128 v[192:195], v137 offset:55296
	ds_read_b128 v[196:199], v137 offset:56320
	global_load_lds_dwordx4 v[200:201], off
	v_lshl_add_u64 v[200:201], v[250:251], 0, s[92:93]
	s_mov_b32 m0, s36
	s_nop 0
	global_load_lds_dwordx4 v[200:201], off
	s_barrier
	s_waitcnt lgkmcnt(0)
	s_setprio 1
	s_waitcnt lgkmcnt(0)
	s_cmp_lg_u32 s99, 0
	s_cbranch_scc1 .La3_skip7
	v_mfma_f32_16x16x32_bf16 v[62:65], v[138:141], v[154:157], v[62:65]
	v_mfma_f32_16x16x32_bf16 v[58:61], v[146:149], v[154:157], v[58:61]
	v_mfma_f32_16x16x32_bf16 v[50:53], v[138:141], v[176:179], v[50:53]
	v_mfma_f32_16x16x32_bf16 v[42:45], v[146:149], v[176:179], v[42:45]
	v_mfma_f32_16x16x32_bf16 v[34:37], v[138:141], v[184:187], v[34:37]
	v_mfma_f32_16x16x32_bf16 v[26:29], v[146:149], v[184:187], v[26:29]
	v_mfma_f32_16x16x32_bf16 v[18:21], v[138:141], v[192:195], v[18:21]
	v_mfma_f32_16x16x32_bf16 v[10:13], v[146:149], v[192:195], v[10:13]
	v_mfma_f32_16x16x32_bf16 v[62:65], v[142:145], v[158:161], v[62:65]
	v_mfma_f32_16x16x32_bf16 v[58:61], v[150:153], v[158:161], v[58:61]
	v_mfma_f32_16x16x32_bf16 v[50:53], v[142:145], v[180:183], v[50:53]
	v_mfma_f32_16x16x32_bf16 v[42:45], v[150:153], v[180:183], v[42:45]
	v_mfma_f32_16x16x32_bf16 v[34:37], v[142:145], v[188:191], v[34:37]
	v_mfma_f32_16x16x32_bf16 v[26:29], v[150:153], v[188:191], v[26:29]
	v_mfma_f32_16x16x32_bf16 v[18:21], v[142:145], v[196:199], v[18:21]
	v_mfma_f32_16x16x32_bf16 v[10:13], v[150:153], v[196:199], v[10:13]
